# stack8 + seams: the workspace pointer the arriving leader needs is fetched ahead of the workgroup barrier (scalar load off the leader's serial arrival chain)
# baseline (speedup 1.0000x reference)
.LBB0_111:
	s_movk_i32 s5, 0xa0
	s_getreg_b32 s4, hwreg(HW_REG_XCC_ID, 0, 4)
	s_load_dwordx2 s[100:101], s[58:59], s5 offset:0x0
	s_waitcnt vmcnt(0)
	s_waitcnt lgkmcnt(0)
	s_waitcnt lgkmcnt(0)
	s_barrier
	s_and_saveexec_b64 s[0:1], s[2:3]
	s_cbranch_execz .LBB0_163
	s_mov_b64 s[2:3], s[100:101]
	s_add_i32 s5, 0, 0x24c20
	v_mov_b32_e32 v0, s5
	s_waitcnt vmcnt(0) expcnt(0) lgkmcnt(0)
	ds_read_b32 v2, v0
	s_add_i32 s5, 0, 0x24c24
	v_mov_b32_e32 v0, s5
	ds_read_b32 v0, v0
	s_and_b32 s46, s4, 15
	s_waitcnt lgkmcnt(1)
	v_cmp_ne_u32_e32 vcc, 0, v2
	s_cbranch_vccnz .LBB0_127
	s_add_u32 s4, s2, 0x4200
	s_addc_u32 s5, s3, 0
	s_add_u32 s6, s2, 0x4400
	s_addc_u32 s7, s3, 0
	s_add_u32 s8, s2, 0x4500
	s_addc_u32 s9, s3, 0
	s_add_u32 s10, s2, 0x4600
	s_addc_u32 s11, s3, 0
	s_add_u32 s12, s2, 0x4700
	s_addc_u32 s13, s3, 0
	s_add_u32 s14, s2, 0x4800
	s_addc_u32 s15, s3, 0
	s_add_u32 s16, s2, 0x4900
	s_addc_u32 s17, s3, 0
	s_add_u32 s18, s2, 0x4a00
	s_addc_u32 s19, s3, 0
	s_add_u32 s20, s2, 0x4b00
	s_addc_u32 s21, s3, 0
	s_add_u32 s22, s2, 0x4c00
	s_addc_u32 s23, s3, 0
	s_add_u32 s24, s2, 0x4d00
	s_addc_u32 s25, s3, 0
	s_add_u32 s26, s2, 0x4e00
	s_addc_u32 s27, s3, 0
	s_add_u32 s28, s2, 0x4f00
	s_addc_u32 s29, s3, 0
	s_add_u32 s30, s2, 0x5000
	s_addc_u32 s31, s3, 0
	s_add_u32 s34, s2, 0x5100
	s_addc_u32 s35, s3, 0
	s_add_u32 s36, s2, 0x5200
	s_addc_u32 s37, s3, 0
	s_mul_i32 s47, s79, s33
	s_add_u32 s38, s2, 0x5300
	s_mul_i32 s47, s47, s78
	s_addc_u32 s39, s3, 0
	s_mov_b32 s48, 1
	v_mov_b32_e32 v16, 0
	s_branch .LBB0_115

.LBB0_250:
	s_waitcnt lgkmcnt(0)
	s_movk_i32 s5, 0xa0
	s_getreg_b32 s4, hwreg(HW_REG_XCC_ID, 0, 4)
	s_load_dwordx2 s[100:101], s[58:59], s5 offset:0x0
	s_waitcnt vmcnt(0)
	s_waitcnt vmcnt(0) lgkmcnt(0)
	s_waitcnt lgkmcnt(0)
	s_barrier
	s_and_saveexec_b64 s[0:1], s[2:3]
	s_cbranch_execz .LBB0_302
	s_mov_b64 s[2:3], s[100:101]
	v_readlane_b32 s5, v255, 13
	s_waitcnt vmcnt(0) expcnt(0) lgkmcnt(0)
	s_and_b32 s49, s4, 15
	v_mov_b32_e32 v0, s5
	ds_read_b32 v3, v0
	v_readlane_b32 s5, v255, 14
	s_waitcnt lgkmcnt(0)
	v_cmp_ne_u32_e32 vcc, 0, v3
	v_mov_b32_e32 v0, s5
	ds_read_b32 v0, v0
	s_cbranch_vccnz .LBB0_266
	s_add_u32 s4, s2, 0x4200
	s_addc_u32 s5, s3, 0
	s_add_u32 s8, s2, 0x4400
	s_addc_u32 s9, s3, 0
	s_add_u32 s10, s2, 0x4500
	s_addc_u32 s11, s3, 0
	s_add_u32 s12, s2, 0x4600
	s_addc_u32 s13, s3, 0
	s_add_u32 s14, s2, 0x4700
	s_addc_u32 s15, s3, 0
	s_add_u32 s16, s2, 0x4800
	s_addc_u32 s17, s3, 0
	s_add_u32 s18, s2, 0x4900
	s_addc_u32 s19, s3, 0
	s_add_u32 s20, s2, 0x4a00
	s_addc_u32 s21, s3, 0
	s_add_u32 s22, s2, 0x4b00
	s_addc_u32 s23, s3, 0
	s_add_u32 s24, s2, 0x4c00
	s_addc_u32 s25, s3, 0
	s_add_u32 s26, s2, 0x4d00
	s_addc_u32 s27, s3, 0
	s_add_u32 s28, s2, 0x4e00
	s_addc_u32 s29, s3, 0
	s_add_u32 s30, s2, 0x4f00
	s_addc_u32 s31, s3, 0
	s_add_u32 s34, s2, 0x5000
	s_addc_u32 s35, s3, 0
	s_add_u32 s36, s2, 0x5100
	s_addc_u32 s37, s3, 0
	s_add_u32 s38, s2, 0x5200
	s_addc_u32 s39, s3, 0
	s_add_u32 s40, s2, 0x5300
	s_addc_u32 s41, s3, 0
	s_mov_b32 s50, 1
	s_branch .LBB0_254

.LBB0_527:
	s_movk_i32 s5, 0xa0
	s_getreg_b32 s4, hwreg(HW_REG_XCC_ID, 0, 4)
	s_load_dwordx2 s[100:101], s[58:59], s5 offset:0x0
	s_waitcnt vmcnt(0)
	s_waitcnt vmcnt(0)
	s_waitcnt lgkmcnt(0)
	s_barrier
	s_and_saveexec_b64 s[0:1], s[2:3]
	s_cbranch_execz .LBB0_579
	s_mov_b64 s[2:3], s[100:101]
	v_readlane_b32 s5, v255, 13
	s_waitcnt vmcnt(0) expcnt(0) lgkmcnt(0)
	s_and_b32 s46, s4, 15
	v_mov_b32_e32 v0, s5
	ds_read_b32 v3, v0
	v_readlane_b32 s5, v255, 14
	s_waitcnt lgkmcnt(0)
	v_cmp_ne_u32_e32 vcc, 0, v3
	v_mov_b32_e32 v0, s5
	ds_read_b32 v0, v0
	s_cbranch_vccnz .LBB0_543
	s_add_u32 s4, s2, 0x4200
	s_addc_u32 s5, s3, 0
	s_add_u32 s6, s2, 0x4400
	s_addc_u32 s7, s3, 0
	s_add_u32 s8, s2, 0x4500
	s_addc_u32 s9, s3, 0
	s_add_u32 s10, s2, 0x4600
	s_addc_u32 s11, s3, 0
	s_add_u32 s12, s2, 0x4700
	s_addc_u32 s13, s3, 0
	s_add_u32 s14, s2, 0x4800
	s_addc_u32 s15, s3, 0
	s_add_u32 s16, s2, 0x4900
	s_addc_u32 s17, s3, 0
	s_add_u32 s18, s2, 0x4a00
	s_addc_u32 s19, s3, 0
	s_add_u32 s20, s2, 0x4b00
	s_addc_u32 s21, s3, 0
	s_add_u32 s22, s2, 0x4c00
	s_addc_u32 s23, s3, 0
	s_add_u32 s24, s2, 0x4d00
	s_addc_u32 s25, s3, 0
	s_add_u32 s26, s2, 0x4e00
	s_addc_u32 s27, s3, 0
	s_add_u32 s28, s2, 0x4f00
	s_addc_u32 s29, s3, 0
	s_add_u32 s30, s2, 0x5000
	s_addc_u32 s31, s3, 0
	s_add_u32 s34, s2, 0x5100
	s_addc_u32 s35, s3, 0
	s_add_u32 s36, s2, 0x5200
	s_addc_u32 s37, s3, 0
	s_add_u32 s38, s2, 0x5300
	s_addc_u32 s39, s3, 0
	s_mov_b32 s47, 1
	s_branch .LBB0_531

.LBB0_630:
	s_waitcnt lgkmcnt(0)
	s_movk_i32 s5, 0xa0
	s_getreg_b32 s4, hwreg(HW_REG_XCC_ID, 0, 4)
	s_load_dwordx2 s[100:101], s[58:59], s5 offset:0x0
	s_waitcnt vmcnt(0)
	s_waitcnt lgkmcnt(0)
	s_barrier
	s_and_saveexec_b64 s[0:1], s[2:3]
	s_cbranch_execz .LBB0_682
	s_mov_b64 s[2:3], s[100:101]
	v_readlane_b32 s5, v255, 13
	s_waitcnt vmcnt(0) expcnt(0) lgkmcnt(0)
	s_and_b32 s47, s4, 15
	v_mov_b32_e32 v0, s5
	ds_read_b32 v3, v0
	v_readlane_b32 s5, v255, 14
	s_waitcnt lgkmcnt(0)
	v_cmp_ne_u32_e32 vcc, 0, v3
	v_mov_b32_e32 v0, s5
	ds_read_b32 v0, v0
	s_cbranch_vccnz .LBB0_646
	s_add_u32 s4, s2, 0x4200
	s_addc_u32 s5, s3, 0
	s_add_u32 s6, s2, 0x4400
	s_addc_u32 s7, s3, 0
	s_add_u32 s8, s2, 0x4500
	s_addc_u32 s9, s3, 0
	s_add_u32 s10, s2, 0x4600
	s_addc_u32 s11, s3, 0
	s_add_u32 s12, s2, 0x4700
	s_addc_u32 s13, s3, 0
	s_add_u32 s14, s2, 0x4800
	s_addc_u32 s15, s3, 0
	s_add_u32 s16, s2, 0x4900
	s_addc_u32 s17, s3, 0
	s_add_u32 s18, s2, 0x4a00
	s_addc_u32 s19, s3, 0
	s_add_u32 s20, s2, 0x4b00
	s_addc_u32 s21, s3, 0
	s_add_u32 s22, s2, 0x4c00
	s_addc_u32 s23, s3, 0
	s_add_u32 s24, s2, 0x4d00
	s_addc_u32 s25, s3, 0
	s_add_u32 s26, s2, 0x4e00
	s_addc_u32 s27, s3, 0
	s_add_u32 s28, s2, 0x4f00
	s_addc_u32 s29, s3, 0
	s_add_u32 s30, s2, 0x5000
	s_addc_u32 s31, s3, 0
	s_add_u32 s34, s2, 0x5100
	s_addc_u32 s35, s3, 0
	s_add_u32 s36, s2, 0x5200
	s_addc_u32 s37, s3, 0
	s_add_u32 s38, s2, 0x5300
	s_addc_u32 s39, s3, 0
	s_mov_b32 s48, 1
	s_branch .LBB0_634

.LBB0_748:
	s_movk_i32 s5, 0xa0
	s_getreg_b32 s4, hwreg(HW_REG_XCC_ID, 0, 4)
	s_load_dwordx2 s[100:101], s[58:59], s5 offset:0x0
	s_waitcnt vmcnt(0)
	s_waitcnt vmcnt(0)
	s_waitcnt lgkmcnt(0)
	s_barrier
	s_and_saveexec_b64 s[0:1], s[2:3]
	s_cbranch_execz .LBB0_800
	s_mov_b64 s[2:3], s[100:101]
	v_readlane_b32 s5, v255, 13
	s_waitcnt vmcnt(0) expcnt(0) lgkmcnt(0)
	s_and_b32 s47, s4, 15
	v_mov_b32_e32 v0, s5
	ds_read_b32 v3, v0
	v_readlane_b32 s5, v255, 14
	s_waitcnt lgkmcnt(0)
	v_cmp_ne_u32_e32 vcc, 0, v3
	v_mov_b32_e32 v0, s5
	ds_read_b32 v0, v0
	s_cbranch_vccnz .LBB0_764
	s_add_u32 s4, s2, 0x4200
	s_addc_u32 s5, s3, 0
	s_add_u32 s6, s2, 0x4400
	s_addc_u32 s7, s3, 0
	s_add_u32 s8, s2, 0x4500
	s_addc_u32 s9, s3, 0
	s_add_u32 s10, s2, 0x4600
	s_addc_u32 s11, s3, 0
	s_add_u32 s12, s2, 0x4700
	s_addc_u32 s13, s3, 0
	s_add_u32 s14, s2, 0x4800
	s_addc_u32 s15, s3, 0
	s_add_u32 s16, s2, 0x4900
	s_addc_u32 s17, s3, 0
	s_add_u32 s18, s2, 0x4a00
	s_addc_u32 s19, s3, 0
	s_add_u32 s20, s2, 0x4b00
	s_addc_u32 s21, s3, 0
	s_add_u32 s22, s2, 0x4c00
	s_addc_u32 s23, s3, 0
	s_add_u32 s24, s2, 0x4d00
	s_addc_u32 s25, s3, 0
	s_add_u32 s26, s2, 0x4e00
	s_addc_u32 s27, s3, 0
	s_add_u32 s28, s2, 0x4f00
	s_addc_u32 s29, s3, 0
	s_add_u32 s30, s2, 0x5000
	s_addc_u32 s31, s3, 0
	s_add_u32 s34, s2, 0x5100
	s_addc_u32 s35, s3, 0
	s_add_u32 s36, s2, 0x5200
	s_addc_u32 s37, s3, 0
	s_add_u32 s38, s2, 0x5300
	s_addc_u32 s39, s3, 0
	s_mov_b32 s48, 1
	s_branch .LBB0_752

.LBB0_820:
	s_movk_i32 s5, 0xa0
	s_getreg_b32 s4, hwreg(HW_REG_XCC_ID, 0, 4)
	s_load_dwordx2 s[100:101], s[58:59], s5 offset:0x0
	s_waitcnt vmcnt(0)
	s_waitcnt lgkmcnt(0)
	s_barrier
	s_and_saveexec_b64 s[0:1], s[2:3]
	s_cbranch_execz .LBB0_872
	s_mov_b64 s[2:3], s[100:101]
	v_readlane_b32 s5, v255, 13
	s_waitcnt vmcnt(0) expcnt(0) lgkmcnt(0)
	s_and_b32 s47, s4, 15
	v_mov_b32_e32 v0, s5
	ds_read_b32 v3, v0
	v_readlane_b32 s5, v255, 14
	s_waitcnt lgkmcnt(0)
	v_cmp_ne_u32_e32 vcc, 0, v3
	v_mov_b32_e32 v0, s5
	ds_read_b32 v0, v0
	s_cbranch_vccnz .LBB0_836
	s_add_u32 s4, s2, 0x4200
	s_addc_u32 s5, s3, 0
	s_add_u32 s6, s2, 0x4400
	s_addc_u32 s7, s3, 0
	s_add_u32 s8, s2, 0x4500
	s_addc_u32 s9, s3, 0
	s_add_u32 s10, s2, 0x4600
	s_addc_u32 s11, s3, 0
	s_add_u32 s12, s2, 0x4700
	s_addc_u32 s13, s3, 0
	s_add_u32 s14, s2, 0x4800
	s_addc_u32 s15, s3, 0
	s_add_u32 s16, s2, 0x4900
	s_addc_u32 s17, s3, 0
	s_add_u32 s18, s2, 0x4a00
	s_addc_u32 s19, s3, 0
	s_add_u32 s20, s2, 0x4b00
	s_addc_u32 s21, s3, 0
	s_add_u32 s22, s2, 0x4c00
	s_addc_u32 s23, s3, 0
	s_add_u32 s24, s2, 0x4d00
	s_addc_u32 s25, s3, 0
	s_add_u32 s26, s2, 0x4e00
	s_addc_u32 s27, s3, 0
	s_add_u32 s28, s2, 0x4f00
	s_addc_u32 s29, s3, 0
	s_add_u32 s30, s2, 0x5000
	s_addc_u32 s31, s3, 0
	s_add_u32 s34, s2, 0x5100
	s_addc_u32 s35, s3, 0
	s_add_u32 s36, s2, 0x5200
	s_addc_u32 s37, s3, 0
	s_add_u32 s38, s2, 0x5300
	s_addc_u32 s39, s3, 0
	s_mov_b32 s48, 1
	s_branch .LBB0_824

.LBB0_925:
	s_waitcnt lgkmcnt(0)
	s_movk_i32 s5, 0xa0
	s_getreg_b32 s4, hwreg(HW_REG_XCC_ID, 0, 4)
	s_load_dwordx2 s[100:101], s[58:59], s5 offset:0x0
	s_waitcnt vmcnt(0)
	s_waitcnt lgkmcnt(0)
	s_barrier
	s_and_saveexec_b64 s[0:1], s[2:3]
	s_cbranch_execz .LBB0_166
	s_mov_b64 s[2:3], s[100:101]
	v_readlane_b32 s5, v255, 13
	s_waitcnt vmcnt(0) expcnt(0) lgkmcnt(0)
	s_and_b32 s46, s4, 15
	v_mov_b32_e32 v0, s5
	ds_read_b32 v3, v0
	v_readlane_b32 s5, v255, 14
	s_waitcnt lgkmcnt(0)
	v_cmp_ne_u32_e32 vcc, 0, v3
	v_mov_b32_e32 v0, s5
	ds_read_b32 v0, v0
	s_cbranch_vccnz .LBB0_941
	s_add_u32 s4, s2, 0x4200
	s_addc_u32 s5, s3, 0
	s_add_u32 s6, s2, 0x4400
	s_addc_u32 s7, s3, 0
	s_add_u32 s8, s2, 0x4500
	s_addc_u32 s9, s3, 0
	s_add_u32 s10, s2, 0x4600
	s_addc_u32 s11, s3, 0
	s_add_u32 s12, s2, 0x4700
	s_addc_u32 s13, s3, 0
	s_add_u32 s14, s2, 0x4800
	s_addc_u32 s15, s3, 0
	s_add_u32 s16, s2, 0x4900
	s_addc_u32 s17, s3, 0
	s_add_u32 s18, s2, 0x4a00
	s_addc_u32 s19, s3, 0
	s_add_u32 s20, s2, 0x4b00
	s_addc_u32 s21, s3, 0
	s_add_u32 s22, s2, 0x4c00
	s_addc_u32 s23, s3, 0
	s_add_u32 s24, s2, 0x4d00
	s_addc_u32 s25, s3, 0
	s_add_u32 s26, s2, 0x4e00
	s_addc_u32 s27, s3, 0
	s_add_u32 s28, s2, 0x4f00
	s_addc_u32 s29, s3, 0
	s_add_u32 s30, s2, 0x5000
	s_addc_u32 s31, s3, 0
	s_add_u32 s34, s2, 0x5100
	s_addc_u32 s35, s3, 0
	s_add_u32 s36, s2, 0x5200
	s_addc_u32 s37, s3, 0
	s_add_u32 s38, s2, 0x5300
	s_addc_u32 s39, s3, 0
	s_mov_b32 s47, 1
	s_branch .LBB0_929
